# NA tail reads the context-kv ready counter early so the poll between the NA and MLA units is skipped; the workgroup barrier there no longer waits for the NA output stores
# speedup vs baseline: 1.0039x; 1.0025x over previous
.Lna_nr_c2:
	s_waitcnt lgkmcnt(0)
	s_barrier
	global_load_dwordx2 v[146:147], v218, s[30:31] offset:0
	global_load_dwordx2 v[148:149], v218, s[30:31] offset:16
	global_load_dwordx2 v[150:151], v218, s[30:31] offset:32
	global_load_dwordx2 v[152:153], v218, s[30:31] offset:48
	global_load_dwordx2 v[154:155], v218, s[30:31] offset:64
	global_load_dwordx2 v[156:157], v218, s[30:31] offset:80
	global_load_dwordx2 v[158:159], v218, s[30:31] offset:96
	global_load_dwordx2 v[160:161], v218, s[30:31] offset:112
	s_mov_b64 s[46:47], s[30:31]
	s_add_i32 s10, s10, s9
	s_cmpk_lt_i32 s10, 0x200
	s_cbranch_scc0 .Lna_lastu
	s_lshr_b32 s36, s10, 4
	s_and_b32 s37, s10, 15
	s_mul_i32 s38, s36, 0x88000
	s_add_u32 s38, s38, 0x4700000
	s_add_u32 s12, s4, s38
	s_addc_u32 s13, s5, 0
	s_add_u32 s38, s38, 0x1100000
	s_add_u32 s14, s4, s38
	s_addc_u32 s15, s5, 0
	s_add_u32 s16, s12, 0x80000
	s_addc_u32 s17, s13, 0
	s_add_u32 s18, s14, 0x2000
	s_addc_u32 s19, s15, 0
	s_lshl_b32 s40, s68, 1
	s_add_i32 s38, s37, -1
	s_cmp_lt_u32 s38, 14
	s_cselect_b32 s22, 12, 8
	s_cselect_b32 s39, 1, 0
	s_lshl_b32 s41, s37, 2
	s_add_i32 s42, s41, -4
	s_max_i32 s42, s42, 0
	s_min_i32 s42, s42, 56
	s_sub_i32 s42, s42, s39
	s_add_i32 s43, s41, s40
	s_add_i32 s23, s43, -4
	s_max_i32 s23, s23, 0
	s_min_i32 s23, s23, 56
	s_add_i32 s62, s43, -3
	s_max_i32 s62, s62, 0
	s_min_i32 s62, s62, 56
	s_sub_i32 s62, s62, s23
	s_add_i32 s63, s62, 8
	s_sub_i32 s23, s23, s42
	s_sub_i32 s43, s42, s43
	s_add_i32 s43, s43, 7
	s_mul_i32 s25, s43, 0x150
	s_ashr_i32 s43, s42, 31
	s_lshl_b64 s[44:45], s[42:43], 13
	s_add_u32 s12, s12, s44
	s_addc_u32 s13, s13, s45
	s_lshl_b64 s[44:45], s[42:43], 7
	s_add_u32 s14, s14, s44
	s_addc_u32 s15, s15, s45
	s_lshl_b32 s38, s36, 12
	s_lshl_b32 s39, s37, 8
	s_add_u32 s38, s38, s39
	s_lshl_b32 s38, s38, 7
	s_add_u32 s38, s38, 0x6900000
	s_add_u32 s34, s4, s38
	s_addc_u32 s35, s5, 0
	s_lshr_b32 s38, s36, 3
	s_lshl_b32 s38, s38, 12
	s_add_u32 s38, s38, s39
	s_lshl_b32 s38, s38, 10
	s_and_b32 s40, s36, 7
	s_lshl_b32 s40, s40, 7
	s_add_u32 s38, s38, s40
	s_add_u32 s38, s38, 0x8900000
	s_add_u32 s30, s4, s38
	s_addc_u32 s31, s5, 0
	global_load_dwordx4 v[98:101], v219, s[34:35] offset:0
	global_load_dwordx4 v[102:105], v219, s[34:35] offset:32
	global_load_dwordx4 v[106:109], v219, s[34:35] offset:64
	global_load_dwordx4 v[110:113], v219, s[34:35] offset:96
	global_load_dwordx4 v[34:37], v206, s[12:13]
	s_add_u32 s12, s12, 0x2000
	s_addc_u32 s13, s13, 0
	global_load_dwordx4 v[230:233], v206, s[12:13]
	global_load_dwordx4 v[234:237], v207, s[14:15]
	s_add_u32 s12, s12, 0x2000
	s_addc_u32 s13, s13, 0
	s_add_u32 s14, s14, 0x80
	s_addc_u32 s15, s15, 0
	global_load_dwordx4 v[188:191], v206, s[12:13]
	global_load_dwordx4 v[192:195], v207, s[14:15]
	s_add_u32 s12, s12, 0x2000
	s_addc_u32 s13, s13, 0
	s_add_u32 s14, s14, 0x80
	s_addc_u32 s15, s15, 0
	s_mov_b32 s20, 3
	s_mov_b32 s21, 2
	s_branch .Lna_nopf
.Lna_lastu:
	v_mov_b32_e32 v227, 0xc000
	global_load_dword v227, v227, s[4:5] sc1
.Lna_nopf:
	v_exp_f32_e32 v66, v66
	v_exp_f32_e32 v67, v67
	v_exp_f32_e32 v68, v68
	v_exp_f32_e32 v69, v69
	v_add_f32_e32 v213, v213, v66
	v_add_f32_e32 v214, v214, v67
	v_add_f32_e32 v213, v213, v68
	v_add_f32_e32 v214, v214, v69
	v_exp_f32_e32 v70, v70
	ds_read_b64 v[162:163], v202 offset:8704
	ds_read_b64 v[164:165], v202 offset:8720
	ds_read_b64 v[166:167], v202 offset:13056
	ds_read_b64 v[168:169], v202 offset:13072
	ds_read_b64 v[170:171], v202 offset:8736
	ds_read_b64 v[172:173], v202 offset:8752
	ds_read_b64 v[174:175], v202 offset:13088
	ds_read_b64 v[176:177], v202 offset:13104
	v_exp_f32_e32 v71, v71
	v_exp_f32_e32 v72, v72
	v_exp_f32_e32 v73, v73
	v_add_f32_e32 v213, v213, v70
	v_add_f32_e32 v214, v214, v71
	v_add_f32_e32 v213, v213, v72
	v_add_f32_e32 v214, v214, v73
	v_cvt_pk_bf16_f32 v66, v66, v67
	v_cvt_pk_bf16_f32 v67, v68, v69
	v_cvt_pk_bf16_f32 v68, v70, v71
	v_cvt_pk_bf16_f32 v69, v72, v73
	s_waitcnt lgkmcnt(6)
	s_nop 0
	v_mfma_f32_32x32x16_bf16 v[2:17], v[162:165], v[66:69], v[2:17]
	ds_read_b64 v[162:163], v202 offset:8768
	ds_read_b64 v[164:165], v202 offset:8784
	s_waitcnt lgkmcnt(6)
	v_mfma_f32_32x32x16_bf16 v[18:33], v[166:169], v[66:69], v[18:33]
	ds_read_b64 v[166:167], v202 offset:13120
	ds_read_b64 v[168:169], v202 offset:13136
	v_exp_f32_e32 v74, v74
	v_exp_f32_e32 v75, v75
	v_exp_f32_e32 v76, v76
	v_exp_f32_e32 v77, v77
	v_add_f32_e32 v213, v213, v74
	v_add_f32_e32 v214, v214, v75
	v_add_f32_e32 v213, v213, v76
	v_add_f32_e32 v214, v214, v77
	v_exp_f32_e32 v78, v78
	v_exp_f32_e32 v79, v79
	v_exp_f32_e32 v80, v80
	v_exp_f32_e32 v81, v81
	v_add_f32_e32 v213, v213, v78
	v_add_f32_e32 v214, v214, v79
	v_add_f32_e32 v213, v213, v80
	v_add_f32_e32 v214, v214, v81
	v_cvt_pk_bf16_f32 v74, v74, v75
	v_cvt_pk_bf16_f32 v75, v76, v77
	v_cvt_pk_bf16_f32 v76, v78, v79
	v_cvt_pk_bf16_f32 v77, v80, v81
	s_waitcnt lgkmcnt(6)
	s_nop 0
	v_mfma_f32_32x32x16_bf16 v[2:17], v[170:173], v[74:77], v[2:17]
	ds_read_b64 v[170:171], v202 offset:8800
	ds_read_b64 v[172:173], v202 offset:8816
	s_waitcnt lgkmcnt(6)
	v_mfma_f32_32x32x16_bf16 v[18:33], v[174:177], v[74:77], v[18:33]
	ds_read_b64 v[174:175], v202 offset:13152
	ds_read_b64 v[176:177], v202 offset:13168
	v_exp_f32_e32 v82, v82
	v_exp_f32_e32 v83, v83
	v_exp_f32_e32 v84, v84
	v_exp_f32_e32 v85, v85
	v_add_f32_e32 v213, v213, v82
	v_add_f32_e32 v214, v214, v83
	v_add_f32_e32 v213, v213, v84
	v_add_f32_e32 v214, v214, v85
	v_exp_f32_e32 v86, v86
	v_exp_f32_e32 v87, v87
	v_exp_f32_e32 v88, v88
	v_exp_f32_e32 v89, v89
	v_add_f32_e32 v213, v213, v86
	v_add_f32_e32 v214, v214, v87
	v_add_f32_e32 v213, v213, v88
	v_add_f32_e32 v214, v214, v89
	v_cvt_pk_bf16_f32 v82, v82, v83
	v_cvt_pk_bf16_f32 v83, v84, v85
	v_cvt_pk_bf16_f32 v84, v86, v87
	v_cvt_pk_bf16_f32 v85, v88, v89
	s_waitcnt lgkmcnt(6)
	s_nop 0
	v_mfma_f32_32x32x16_bf16 v[2:17], v[162:165], v[82:85], v[2:17]
	s_waitcnt lgkmcnt(4)
	v_mfma_f32_32x32x16_bf16 v[18:33], v[166:169], v[82:85], v[18:33]
	v_exp_f32_e32 v90, v90
	v_exp_f32_e32 v91, v91
	v_exp_f32_e32 v92, v92
	v_exp_f32_e32 v93, v93
	v_add_f32_e32 v213, v213, v90
	v_add_f32_e32 v214, v214, v91
	v_add_f32_e32 v213, v213, v92
	v_add_f32_e32 v214, v214, v93
	v_exp_f32_e32 v94, v94
	v_exp_f32_e32 v95, v95
	v_exp_f32_e32 v96, v96
	v_exp_f32_e32 v97, v97
	v_add_f32_e32 v213, v213, v94
	v_add_f32_e32 v214, v214, v95
	v_add_f32_e32 v213, v213, v96
	v_add_f32_e32 v214, v214, v97
	v_cvt_pk_bf16_f32 v90, v90, v91
	v_cvt_pk_bf16_f32 v91, v92, v93
	v_cvt_pk_bf16_f32 v92, v94, v95
	v_cvt_pk_bf16_f32 v93, v96, v97
	s_waitcnt lgkmcnt(2)
	s_nop 0
	v_mfma_f32_32x32x16_bf16 v[2:17], v[170:173], v[90:93], v[2:17]
	s_waitcnt lgkmcnt(0)
	v_mfma_f32_32x32x16_bf16 v[18:33], v[174:177], v[90:93], v[18:33]
	s_waitcnt lgkmcnt(0)
	s_barrier
	v_add_f32_e32 v213, v213, v214
	v_mov_b32_e32 v217, v213
	s_nop 1
	v_permlane32_swap_b32_e32 v213, v217
	v_add_f32_e32 v216, v213, v217
	v_div_scale_f32 v217, s[36:37], v216, v216, 1.0
	v_rcp_f32_e32 v223, v217
	v_div_scale_f32 v224, vcc, 1.0, v216, 1.0
	v_fma_f32 v225, -v217, v223, 1.0
	v_fmac_f32_e32 v223, v225, v223
	v_mul_f32_e32 v225, v224, v223
	v_fma_f32 v226, -v217, v225, v224
	v_fmac_f32_e32 v225, v226, v223
	v_fma_f32 v217, -v217, v225, v224
	v_div_fmas_f32 v217, v217, v223, v225
	v_div_fixup_f32 v216, v217, v216, 1.0
	s_nop 15
	v_mul_f32_e32 v2, v2, v216
	v_mul_f32_e32 v3, v3, v216
	v_mul_f32_e32 v4, v4, v216
	v_mul_f32_e32 v5, v5, v216
	v_mul_f32_e32 v6, v6, v216
	v_mul_f32_e32 v7, v7, v216
	v_mul_f32_e32 v8, v8, v216
	v_mul_f32_e32 v9, v9, v216
	v_mul_f32_e32 v10, v10, v216
	v_mul_f32_e32 v11, v11, v216
	v_mul_f32_e32 v12, v12, v216
	v_mul_f32_e32 v13, v13, v216
	v_mul_f32_e32 v14, v14, v216
	v_mul_f32_e32 v15, v15, v216
	v_mul_f32_e32 v16, v16, v216
	v_mul_f32_e32 v17, v17, v216
	v_mul_f32_e32 v18, v18, v216
	v_mul_f32_e32 v19, v19, v216
	v_mul_f32_e32 v20, v20, v216
	v_mul_f32_e32 v21, v21, v216
	v_mul_f32_e32 v22, v22, v216
	v_mul_f32_e32 v23, v23, v216
	v_mul_f32_e32 v24, v24, v216
	v_mul_f32_e32 v25, v25, v216
	v_mul_f32_e32 v26, v26, v216
	v_mul_f32_e32 v27, v27, v216
	v_mul_f32_e32 v28, v28, v216
	v_mul_f32_e32 v29, v29, v216
	v_mul_f32_e32 v30, v30, v216
	v_mul_f32_e32 v31, v31, v216
	v_mul_f32_e32 v32, v32, v216
	v_mul_f32_e32 v33, v33, v216
	s_cmpk_lt_i32 s10, 0x200
	s_cbranch_scc1 .Lna_zw9
	s_waitcnt vmcnt(1)
	s_branch .Lna_zw

.Lna_exit:
	s_waitcnt vmcnt(8)
	v_readfirstlane_b32 s36, v227
	s_nop 3
	v_writelane_b32 v250, s36, 12
	s_mov_b32 s88, s9
.LBB0_1875:
	s_mov_b64 s[0:1], exec
	v_readlane_b32 s52, v251, 24
	v_readlane_b32 s53, v251, 25
	v_readlane_b32 s90, v251, 42
	v_readlane_b32 s56, v251, 26
	v_readlane_b32 s76, v251, 44
	v_readlane_b32 s46, v251, 63
	s_and_b64 s[4:5], s[0:1], s[52:53]
	v_readlane_b32 s87, v251, 52
	v_readlane_b32 s91, v251, 43
	v_readlane_b32 s57, v251, 27
	v_readlane_b32 s77, v251, 45
	v_readlane_b32 s78, v251, 46
	v_readlane_b32 s79, v251, 47
	v_readlane_b32 s80, v251, 48
	v_readlane_b32 s81, v251, 49
	v_readlane_b32 s82, v251, 50
	v_readlane_b32 s83, v251, 51
	v_readlane_b32 s47, v250, 0
	v_readlane_b32 s2, v251, 61
	v_readlane_b32 s58, v251, 28
	v_readlane_b32 s59, v251, 29
	v_readlane_b32 s60, v251, 30
	v_readlane_b32 s61, v251, 31
	v_readlane_b32 s62, v251, 32
	v_readlane_b32 s63, v251, 33
	v_readlane_b32 s64, v251, 34
	v_readlane_b32 s65, v251, 35
	v_readlane_b32 s66, v251, 36
	v_readlane_b32 s67, v251, 37
	v_readlane_b32 s68, v251, 38
	v_readlane_b32 s69, v251, 39
	v_readlane_b32 s70, v251, 40
	v_readlane_b32 s71, v251, 41
	s_mov_b64 exec, s[4:5]
	s_cbranch_execz .LBB0_1885
	v_readlane_b32 s4, v250, 12
	s_nop 3
	s_cmp_gt_u32 s4, 15
	s_cbranch_scc1 .LBB0_1884
	s_add_u32 s4, s80, 0xc000
	s_addc_u32 s5, s81, 0
	s_mov_b32 s3, 0x400001
	v_mov_b32_e32 v2, 0
	s_branch .LBB0_1878

.LBB0_1885:
	s_or_b64 exec, exec, s[0:1]
	v_readlane_b32 s0, v250, 2
	v_readlane_b32 s1, v250, 3
	v_readlane_b32 s86, v250, 1
	s_andn2_b64 vcc, exec, s[0:1]
	s_waitcnt lgkmcnt(0)
	s_barrier
	s_cbranch_vccnz .LBB0_1920
	v_and_b32_e32 v234, 31, v0
	v_bfe_u32 v235, v0, 5, 1
	v_mul_u32_u24_e32 v220, 0xd0, v234
	v_lshl_add_u32 v220, v235, 4, v220
	v_mul_u32_u24_e32 v221, 0x90, v234
	v_lshl_add_u32 v221, v235, 4, v221
	v_add_u32_e32 v221, 0xd000, v221
	v_lshl_or_b32 v1, s87, 5, v234
	v_mul_u32_u24_e32 v237, 0xc0, v1
	v_lshl_add_u32 v237, v235, 4, v237
	v_lshlrev_b32_e32 v236, 10, v1
	v_lshl_add_u32 v236, v235, 3, v236
	v_lshlrev_b32_e32 v226, 4, v0
	v_add_u32_e32 v227, 0x2000, v226
	v_add_u32_e32 v228, 0x4000, v226
	v_lshrrev_b32_e32 v234, 3, v0
	v_and_b32_e32 v235, 7, v0
	v_mul_u32_u24_e32 v229, 0x2200, v234
	v_lshl_add_u32 v229, v235, 4, v229
	v_mul_u32_u24_e32 v225, 0x90, v234
	v_lshrrev_b32_e32 v1, 1, v235
	v_lshl_add_u32 v225, v1, 5, v225
	v_and_b32_e32 v1, 1, v235
	v_lshl_add_u32 v225, v1, 3, v225
	v_add_u32_e32 v225, 0xd000, v225
	s_mov_b32 s17, 0xaaab
	s_movk_i32 s18, 0xd0
	v_mov_b32_e32 v234, v0
	v_mul_lo_u32 v235, v234, s17
	v_lshrrev_b32_e32 v235, 19, v235
	v_mul_u32_u24_e32 v1, 12, v235
	v_sub_u32_e32 v234, v234, v1
	v_lshrrev_b32_e32 v1, 6, v235
	v_and_b32_e32 v235, 63, v235
	v_mul_u32_u24_e32 v1, 0x3400, v1
	v_mad_u32_u24 v1, v235, s18, v1
	v_lshl_add_u32 v222, v234, 4, v1
	v_add_u32_e32 v234, 512, v0
	v_mul_lo_u32 v235, v234, s17
	v_lshrrev_b32_e32 v235, 19, v235
	v_mul_u32_u24_e32 v1, 12, v235
	v_sub_u32_e32 v234, v234, v1
	v_lshrrev_b32_e32 v1, 6, v235
	v_and_b32_e32 v235, 63, v235
	v_mul_u32_u24_e32 v1, 0x3400, v1
	v_mad_u32_u24 v1, v235, s18, v1
	v_lshl_add_u32 v223, v234, 4, v1
	v_add_u32_e32 v234, 1024, v0
	v_mul_lo_u32 v235, v234, s17
	v_lshrrev_b32_e32 v235, 19, v235
	v_mul_u32_u24_e32 v1, 12, v235
	v_sub_u32_e32 v234, v234, v1
	v_lshrrev_b32_e32 v1, 6, v235
	v_and_b32_e32 v235, 63, v235
	v_mul_u32_u24_e32 v1, 0x3400, v1
	v_mad_u32_u24 v1, v235, s18, v1
	v_lshl_add_u32 v224, v234, 4, v1
	v_mov_b32_e32 v234, 0
	v_mov_b32_e32 v235, 0x186a0
	ds_write_b32 v235, v234
